# score GEMM epilogue: the eight per-row-slot (mean, rstd) loads issued together at the top instead of one load + full vmcnt wait per slot
# speedup vs baseline: 1.0038x; 1.0038x over previous
.LBB0_767:
	v_lshl_or_b32 v178, s17, 8, v182
	v_ashrrev_i32_e32 v179, 31, v178
	v_lshl_add_u32 v176, s50, 8, v180
	v_lshlrev_b64 v[64:65], 2, v[178:179]
	v_ashrrev_i32_e32 v177, 31, v176
	v_lshl_add_u64 v[66:67], s[12:13], 0, v[64:65]
	v_lshl_add_u64 v[72:73], s[10:11], 0, v[64:65]
	v_lshl_add_u64 v[188:189], v[176:177], 3, s[4:5]
	global_load_dwordx4 v[84:87], v[66:67], off offset:16
	global_load_dwordx4 v[92:95], v[66:67], off
	global_load_dwordx4 v[80:83], v[72:73], off offset:16
	global_load_dwordx4 v[88:91], v[72:73], off
	global_load_dwordx4 v[68:71], v[66:67], off offset:528
	global_load_dwordx4 v[76:79], v[66:67], off offset:512
	s_nop 0
	global_load_dwordx4 v[64:67], v[72:73], off offset:528
	s_nop 0
	global_load_dwordx4 v[72:75], v[72:73], off offset:512
	v_lshlrev_b64 v[186:187], 12, v[176:177]
	global_load_dwordx2 v[188:189], v[188:189], off
	v_or_b32_e32 v202, 16, v176
	v_ashrrev_i32_e32 v203, 31, v202
	v_lshl_add_u64 v[202:203], v[202:203], 3, s[4:5]
	global_load_dwordx2 v[202:203], v[202:203], off
	v_or_b32_e32 v204, 32, v176
	v_ashrrev_i32_e32 v205, 31, v204
	v_lshl_add_u64 v[204:205], v[204:205], 3, s[4:5]
	global_load_dwordx2 v[204:205], v[204:205], off
	v_or_b32_e32 v206, 48, v176
	v_ashrrev_i32_e32 v207, 31, v206
	v_lshl_add_u64 v[206:207], v[206:207], 3, s[4:5]
	global_load_dwordx2 v[206:207], v[206:207], off
	v_add_u32_e32 v208, 0x80, v176
	v_ashrrev_i32_e32 v209, 31, v208
	v_lshl_add_u64 v[208:209], v[208:209], 3, s[4:5]
	global_load_dwordx2 v[208:209], v[208:209], off
	v_add_u32_e32 v210, 0x90, v176
	v_ashrrev_i32_e32 v211, 31, v210
	v_lshl_add_u64 v[210:211], v[210:211], 3, s[4:5]
	global_load_dwordx2 v[210:211], v[210:211], off
	v_add_u32_e32 v212, 0xa0, v176
	v_ashrrev_i32_e32 v213, 31, v212
	v_lshl_add_u64 v[212:213], v[212:213], 3, s[4:5]
	global_load_dwordx2 v[212:213], v[212:213], off
	v_add_u32_e32 v214, 0xb0, v176
	v_ashrrev_i32_e32 v215, 31, v214
	v_lshl_add_u64 v[214:215], v[214:215], 3, s[4:5]
	global_load_dwordx2 v[214:215], v[214:215], off
	v_lshl_add_u64 v[186:187], s[92:93], 0, v[186:187]
	v_lshlrev_b64 v[178:179], 1, v[178:179]
	v_lshl_add_u64 v[186:187], v[186:187], 0, v[178:179]
	v_readlane_b32 s68, v246, 58
	s_mov_b64 s[50:51], -1
	s_andn2_b64 vcc, exec, s[40:41]
	v_readlane_b32 s69, v246, 59
	s_waitcnt vmcnt(0)
	v_xor_b32_e32 v87, 0x80000000, v87
	v_xor_b32_e32 v95, 0x80000000, v95
	v_xor_b32_e32 v94, 0x80000000, v94
	v_xor_b32_e32 v86, 0x80000000, v86
	v_xor_b32_e32 v71, 0x80000000, v71
	v_xor_b32_e32 v79, 0x80000000, v79
	v_xor_b32_e32 v78, 0x80000000, v78
	v_xor_b32_e32 v70, 0x80000000, v70
	v_pk_fma_f32 v[156:157], v[92:93], v[188:189], v[156:157] op_sel_hi:[1,0,1] neg_lo:[1,0,0] neg_hi:[1,0,0]
	v_pk_fma_f32 v[158:159], v[94:95], v[188:189], v[158:159] op_sel_hi:[1,0,1]
	v_pk_fma_f32 v[152:153], v[84:85], v[188:189], v[152:153] op_sel_hi:[1,0,1] neg_lo:[1,0,0] neg_hi:[1,0,0]
	v_pk_fma_f32 v[154:155], v[86:87], v[188:189], v[154:155] op_sel_hi:[1,0,1]
	v_pk_fma_f32 v[158:159], v[188:189], v[158:159], v[90:91] op_sel:[1,0,0]
	v_pk_fma_f32 v[156:157], v[188:189], v[156:157], v[88:89] op_sel:[1,0,0]
	v_pk_fma_f32 v[190:191], v[188:189], v[154:155], v[82:83] op_sel:[1,0,0]
	v_pk_fma_f32 v[154:155], v[188:189], v[152:153], v[80:81] op_sel:[1,0,0]
	v_cvt_pk_f16_f32 v152, v156, v157
	v_cvt_pk_f16_f32 v153, v158, v159
	v_cvt_pk_f16_f32 v154, v154, v155
	v_cvt_pk_f16_f32 v155, v190, v191
	v_pk_fma_f32 v[148:149], v[76:77], v[188:189], v[148:149] op_sel_hi:[1,0,1] neg_lo:[1,0,0] neg_hi:[1,0,0]
	v_pk_fma_f32 v[150:151], v[78:79], v[188:189], v[150:151] op_sel_hi:[1,0,1]
	v_pk_fma_f32 v[144:145], v[68:69], v[188:189], v[144:145] op_sel_hi:[1,0,1] neg_lo:[1,0,0] neg_hi:[1,0,0]
	v_pk_fma_f32 v[146:147], v[70:71], v[188:189], v[146:147] op_sel_hi:[1,0,1]
	global_store_dwordx4 v[186:187], v[152:155], off
	v_pk_fma_f32 v[150:151], v[188:189], v[150:151], v[74:75] op_sel:[1,0,0]
	v_pk_fma_f32 v[148:149], v[188:189], v[148:149], v[72:73] op_sel:[1,0,0]
	v_pk_fma_f32 v[152:153], v[188:189], v[146:147], v[66:67] op_sel:[1,0,0]
	v_pk_fma_f32 v[146:147], v[188:189], v[144:145], v[64:65] op_sel:[1,0,0]
	v_cvt_pk_f16_f32 v144, v148, v149
	v_cvt_pk_f16_f32 v145, v150, v151
	v_cvt_pk_f16_f32 v146, v146, v147
	v_cvt_pk_f16_f32 v147, v152, v153
	global_store_dwordx4 v[186:187], v[144:147], off offset:256
	s_nop 1
	v_or_b32_e32 v144, 16, v176
	v_ashrrev_i32_e32 v145, 31, v144
	v_lshlrev_b64 v[146:147], 12, v[144:145]
	v_lshl_add_u64 v[144:145], v[144:145], 3, s[4:5]
	v_mov_b32_e32 v144, v202
	v_mov_b32_e32 v145, v203
	v_lshl_add_u64 v[146:147], s[92:93], 0, v[146:147]
	v_lshl_add_u64 v[146:147], v[146:147], 0, v[178:179]
	v_pk_fma_f32 v[140:141], v[92:93], v[144:145], v[140:141] op_sel_hi:[1,0,1] neg_lo:[1,0,0] neg_hi:[1,0,0]
	v_pk_fma_f32 v[142:143], v[94:95], v[144:145], v[142:143] op_sel_hi:[1,0,1]
	v_pk_fma_f32 v[136:137], v[84:85], v[144:145], v[136:137] op_sel_hi:[1,0,1] neg_lo:[1,0,0] neg_hi:[1,0,0]
	v_pk_fma_f32 v[138:139], v[86:87], v[144:145], v[138:139] op_sel_hi:[1,0,1]
	v_pk_fma_f32 v[142:143], v[144:145], v[142:143], v[90:91] op_sel:[1,0,0]
	v_pk_fma_f32 v[140:141], v[144:145], v[140:141], v[88:89] op_sel:[1,0,0]
	v_pk_fma_f32 v[148:149], v[144:145], v[138:139], v[82:83] op_sel:[1,0,0]
	v_pk_fma_f32 v[138:139], v[144:145], v[136:137], v[80:81] op_sel:[1,0,0]
	v_cvt_pk_f16_f32 v136, v140, v141
	v_cvt_pk_f16_f32 v137, v142, v143
	v_cvt_pk_f16_f32 v138, v138, v139
	v_cvt_pk_f16_f32 v139, v148, v149
	v_pk_fma_f32 v[132:133], v[76:77], v[144:145], v[132:133] op_sel_hi:[1,0,1] neg_lo:[1,0,0] neg_hi:[1,0,0]
	v_pk_fma_f32 v[134:135], v[78:79], v[144:145], v[134:135] op_sel_hi:[1,0,1]
	v_pk_fma_f32 v[128:129], v[68:69], v[144:145], v[128:129] op_sel_hi:[1,0,1] neg_lo:[1,0,0] neg_hi:[1,0,0]
	v_pk_fma_f32 v[130:131], v[70:71], v[144:145], v[130:131] op_sel_hi:[1,0,1]
	global_store_dwordx4 v[146:147], v[136:139], off
	v_pk_fma_f32 v[134:135], v[144:145], v[134:135], v[74:75] op_sel:[1,0,0]
	v_pk_fma_f32 v[132:133], v[144:145], v[132:133], v[72:73] op_sel:[1,0,0]
	v_pk_fma_f32 v[136:137], v[144:145], v[130:131], v[66:67] op_sel:[1,0,0]
	v_pk_fma_f32 v[130:131], v[144:145], v[128:129], v[64:65] op_sel:[1,0,0]
	v_cvt_pk_f16_f32 v128, v132, v133
	v_cvt_pk_f16_f32 v129, v134, v135
	v_cvt_pk_f16_f32 v130, v130, v131
	v_cvt_pk_f16_f32 v131, v136, v137
	global_store_dwordx4 v[146:147], v[128:131], off offset:256
	s_nop 1
	v_or_b32_e32 v128, 32, v176
	v_ashrrev_i32_e32 v129, 31, v128
	v_lshlrev_b64 v[130:131], 12, v[128:129]
	v_lshl_add_u64 v[128:129], v[128:129], 3, s[4:5]
	v_mov_b32_e32 v128, v204
	v_mov_b32_e32 v129, v205
	v_lshl_add_u64 v[130:131], s[92:93], 0, v[130:131]
	v_lshl_add_u64 v[130:131], v[130:131], 0, v[178:179]
	v_pk_fma_f32 v[124:125], v[92:93], v[128:129], v[124:125] op_sel_hi:[1,0,1] neg_lo:[1,0,0] neg_hi:[1,0,0]
	v_pk_fma_f32 v[126:127], v[94:95], v[128:129], v[126:127] op_sel_hi:[1,0,1]
	v_pk_fma_f32 v[120:121], v[84:85], v[128:129], v[120:121] op_sel_hi:[1,0,1] neg_lo:[1,0,0] neg_hi:[1,0,0]
	v_pk_fma_f32 v[122:123], v[86:87], v[128:129], v[122:123] op_sel_hi:[1,0,1]
	v_pk_fma_f32 v[126:127], v[128:129], v[126:127], v[90:91] op_sel:[1,0,0]
	v_pk_fma_f32 v[124:125], v[128:129], v[124:125], v[88:89] op_sel:[1,0,0]
	v_pk_fma_f32 v[132:133], v[128:129], v[122:123], v[82:83] op_sel:[1,0,0]
	v_pk_fma_f32 v[122:123], v[128:129], v[120:121], v[80:81] op_sel:[1,0,0]
	v_cvt_pk_f16_f32 v120, v124, v125
	v_cvt_pk_f16_f32 v121, v126, v127
	v_cvt_pk_f16_f32 v122, v122, v123
	v_cvt_pk_f16_f32 v123, v132, v133
	v_pk_fma_f32 v[116:117], v[76:77], v[128:129], v[116:117] op_sel_hi:[1,0,1] neg_lo:[1,0,0] neg_hi:[1,0,0]
	v_pk_fma_f32 v[118:119], v[78:79], v[128:129], v[118:119] op_sel_hi:[1,0,1]
	v_pk_fma_f32 v[112:113], v[68:69], v[128:129], v[112:113] op_sel_hi:[1,0,1] neg_lo:[1,0,0] neg_hi:[1,0,0]
	v_pk_fma_f32 v[114:115], v[70:71], v[128:129], v[114:115] op_sel_hi:[1,0,1]
	global_store_dwordx4 v[130:131], v[120:123], off
	v_pk_fma_f32 v[118:119], v[128:129], v[118:119], v[74:75] op_sel:[1,0,0]
	v_pk_fma_f32 v[116:117], v[128:129], v[116:117], v[72:73] op_sel:[1,0,0]
	v_pk_fma_f32 v[120:121], v[128:129], v[114:115], v[66:67] op_sel:[1,0,0]
	v_pk_fma_f32 v[114:115], v[128:129], v[112:113], v[64:65] op_sel:[1,0,0]
	v_cvt_pk_f16_f32 v112, v116, v117
	v_cvt_pk_f16_f32 v113, v118, v119
	v_cvt_pk_f16_f32 v114, v114, v115
	v_cvt_pk_f16_f32 v115, v120, v121
	global_store_dwordx4 v[130:131], v[112:115], off offset:256
	s_nop 1
	v_or_b32_e32 v112, 48, v176
	v_ashrrev_i32_e32 v113, 31, v112
	v_lshlrev_b64 v[114:115], 12, v[112:113]
	v_lshl_add_u64 v[112:113], v[112:113], 3, s[4:5]
	v_mov_b32_e32 v112, v206
	v_mov_b32_e32 v113, v207
	v_lshl_add_u64 v[114:115], s[92:93], 0, v[114:115]
	v_lshl_add_u64 v[114:115], v[114:115], 0, v[178:179]
	v_pk_fma_f32 v[108:109], v[92:93], v[112:113], v[108:109] op_sel_hi:[1,0,1] neg_lo:[1,0,0] neg_hi:[1,0,0]
	v_pk_fma_f32 v[110:111], v[94:95], v[112:113], v[110:111] op_sel_hi:[1,0,1]
	v_pk_fma_f32 v[104:105], v[84:85], v[112:113], v[104:105] op_sel_hi:[1,0,1] neg_lo:[1,0,0] neg_hi:[1,0,0]
	v_pk_fma_f32 v[106:107], v[86:87], v[112:113], v[106:107] op_sel_hi:[1,0,1]
	v_pk_fma_f32 v[110:111], v[112:113], v[110:111], v[90:91] op_sel:[1,0,0]
	v_pk_fma_f32 v[108:109], v[112:113], v[108:109], v[88:89] op_sel:[1,0,0]
	v_pk_fma_f32 v[116:117], v[112:113], v[106:107], v[82:83] op_sel:[1,0,0]
	v_pk_fma_f32 v[106:107], v[112:113], v[104:105], v[80:81] op_sel:[1,0,0]
	v_cvt_pk_f16_f32 v104, v108, v109
	v_cvt_pk_f16_f32 v105, v110, v111
	v_cvt_pk_f16_f32 v106, v106, v107
	v_cvt_pk_f16_f32 v107, v116, v117
	v_pk_fma_f32 v[100:101], v[76:77], v[112:113], v[100:101] op_sel_hi:[1,0,1] neg_lo:[1,0,0] neg_hi:[1,0,0]
	v_pk_fma_f32 v[102:103], v[78:79], v[112:113], v[102:103] op_sel_hi:[1,0,1]
	v_pk_fma_f32 v[96:97], v[68:69], v[112:113], v[96:97] op_sel_hi:[1,0,1] neg_lo:[1,0,0] neg_hi:[1,0,0]
	v_pk_fma_f32 v[98:99], v[70:71], v[112:113], v[98:99] op_sel_hi:[1,0,1]
	global_store_dwordx4 v[114:115], v[104:107], off
	v_pk_fma_f32 v[102:103], v[112:113], v[102:103], v[74:75] op_sel:[1,0,0]
	v_pk_fma_f32 v[100:101], v[112:113], v[100:101], v[72:73] op_sel:[1,0,0]
	v_pk_fma_f32 v[104:105], v[112:113], v[98:99], v[66:67] op_sel:[1,0,0]
	v_pk_fma_f32 v[98:99], v[112:113], v[96:97], v[64:65] op_sel:[1,0,0]
	v_cvt_pk_f16_f32 v96, v100, v101
	v_cvt_pk_f16_f32 v97, v102, v103
	v_cvt_pk_f16_f32 v98, v98, v99
	v_cvt_pk_f16_f32 v99, v104, v105
	global_store_dwordx4 v[114:115], v[96:99], off offset:256
	s_nop 1
	v_add_u32_e32 v96, 0x80, v176
	v_ashrrev_i32_e32 v97, 31, v96
	v_lshlrev_b64 v[98:99], 12, v[96:97]
	v_lshl_add_u64 v[96:97], v[96:97], 3, s[4:5]
	v_mov_b32_e32 v96, v208
	v_mov_b32_e32 v97, v209
	v_lshl_add_u64 v[98:99], s[92:93], 0, v[98:99]
	v_lshl_add_u64 v[98:99], v[98:99], 0, v[178:179]
	v_pk_fma_f32 v[60:61], v[92:93], v[96:97], v[60:61] op_sel_hi:[1,0,1] neg_lo:[1,0,0] neg_hi:[1,0,0]
	v_pk_fma_f32 v[62:63], v[94:95], v[96:97], v[62:63] op_sel_hi:[1,0,1]
	v_pk_fma_f32 v[56:57], v[84:85], v[96:97], v[56:57] op_sel_hi:[1,0,1] neg_lo:[1,0,0] neg_hi:[1,0,0]
	v_pk_fma_f32 v[58:59], v[86:87], v[96:97], v[58:59] op_sel_hi:[1,0,1]
	v_pk_fma_f32 v[62:63], v[96:97], v[62:63], v[90:91] op_sel:[1,0,0]
	v_pk_fma_f32 v[60:61], v[96:97], v[60:61], v[88:89] op_sel:[1,0,0]
	v_pk_fma_f32 v[100:101], v[96:97], v[58:59], v[82:83] op_sel:[1,0,0]
	v_pk_fma_f32 v[58:59], v[96:97], v[56:57], v[80:81] op_sel:[1,0,0]
	v_cvt_pk_f16_f32 v56, v60, v61
	v_cvt_pk_f16_f32 v57, v62, v63
	v_cvt_pk_f16_f32 v58, v58, v59
	v_cvt_pk_f16_f32 v59, v100, v101
	v_pk_fma_f32 v[52:53], v[76:77], v[96:97], v[52:53] op_sel_hi:[1,0,1] neg_lo:[1,0,0] neg_hi:[1,0,0]
	v_pk_fma_f32 v[54:55], v[78:79], v[96:97], v[54:55] op_sel_hi:[1,0,1]
	v_pk_fma_f32 v[48:49], v[68:69], v[96:97], v[48:49] op_sel_hi:[1,0,1] neg_lo:[1,0,0] neg_hi:[1,0,0]
	v_pk_fma_f32 v[50:51], v[70:71], v[96:97], v[50:51] op_sel_hi:[1,0,1]
	global_store_dwordx4 v[98:99], v[56:59], off
	v_pk_fma_f32 v[54:55], v[96:97], v[54:55], v[74:75] op_sel:[1,0,0]
	v_pk_fma_f32 v[52:53], v[96:97], v[52:53], v[72:73] op_sel:[1,0,0]
	v_pk_fma_f32 v[56:57], v[96:97], v[50:51], v[66:67] op_sel:[1,0,0]
	v_pk_fma_f32 v[50:51], v[96:97], v[48:49], v[64:65] op_sel:[1,0,0]
	v_cvt_pk_f16_f32 v48, v52, v53
	v_cvt_pk_f16_f32 v49, v54, v55
	v_cvt_pk_f16_f32 v50, v50, v51
	v_cvt_pk_f16_f32 v51, v56, v57
	global_store_dwordx4 v[98:99], v[48:51], off offset:256
	s_nop 1
	v_add_u32_e32 v48, 0x90, v176
	v_ashrrev_i32_e32 v49, 31, v48
	v_lshlrev_b64 v[50:51], 12, v[48:49]
	v_lshl_add_u64 v[48:49], v[48:49], 3, s[4:5]
	v_mov_b32_e32 v48, v210
	v_mov_b32_e32 v49, v211
	v_lshl_add_u64 v[50:51], s[92:93], 0, v[50:51]
	v_lshl_add_u64 v[50:51], v[50:51], 0, v[178:179]
	v_pk_fma_f32 v[44:45], v[92:93], v[48:49], v[44:45] op_sel_hi:[1,0,1] neg_lo:[1,0,0] neg_hi:[1,0,0]
	v_pk_fma_f32 v[46:47], v[94:95], v[48:49], v[46:47] op_sel_hi:[1,0,1]
	v_pk_fma_f32 v[40:41], v[84:85], v[48:49], v[40:41] op_sel_hi:[1,0,1] neg_lo:[1,0,0] neg_hi:[1,0,0]
	v_pk_fma_f32 v[42:43], v[86:87], v[48:49], v[42:43] op_sel_hi:[1,0,1]
	v_pk_fma_f32 v[46:47], v[48:49], v[46:47], v[90:91] op_sel:[1,0,0]
	v_pk_fma_f32 v[44:45], v[48:49], v[44:45], v[88:89] op_sel:[1,0,0]
	v_pk_fma_f32 v[52:53], v[48:49], v[42:43], v[82:83] op_sel:[1,0,0]
	v_pk_fma_f32 v[42:43], v[48:49], v[40:41], v[80:81] op_sel:[1,0,0]
	v_cvt_pk_f16_f32 v40, v44, v45
	v_cvt_pk_f16_f32 v41, v46, v47
	v_cvt_pk_f16_f32 v42, v42, v43
	v_cvt_pk_f16_f32 v43, v52, v53
	v_pk_fma_f32 v[36:37], v[76:77], v[48:49], v[36:37] op_sel_hi:[1,0,1] neg_lo:[1,0,0] neg_hi:[1,0,0]
	v_pk_fma_f32 v[38:39], v[78:79], v[48:49], v[38:39] op_sel_hi:[1,0,1]
	v_pk_fma_f32 v[32:33], v[68:69], v[48:49], v[32:33] op_sel_hi:[1,0,1] neg_lo:[1,0,0] neg_hi:[1,0,0]
	v_pk_fma_f32 v[34:35], v[70:71], v[48:49], v[34:35] op_sel_hi:[1,0,1]
	global_store_dwordx4 v[50:51], v[40:43], off
	v_pk_fma_f32 v[38:39], v[48:49], v[38:39], v[74:75] op_sel:[1,0,0]
	v_pk_fma_f32 v[36:37], v[48:49], v[36:37], v[72:73] op_sel:[1,0,0]
	v_pk_fma_f32 v[40:41], v[48:49], v[34:35], v[66:67] op_sel:[1,0,0]
	v_pk_fma_f32 v[34:35], v[48:49], v[32:33], v[64:65] op_sel:[1,0,0]
	v_cvt_pk_f16_f32 v32, v36, v37
	v_cvt_pk_f16_f32 v33, v38, v39
	v_cvt_pk_f16_f32 v34, v34, v35
	v_cvt_pk_f16_f32 v35, v40, v41
	global_store_dwordx4 v[50:51], v[32:35], off offset:256
	s_nop 1
	v_add_u32_e32 v32, 0xa0, v176
	v_ashrrev_i32_e32 v33, 31, v32
	v_lshlrev_b64 v[34:35], 12, v[32:33]
	v_lshl_add_u64 v[32:33], v[32:33], 3, s[4:5]
	v_mov_b32_e32 v32, v212
	v_mov_b32_e32 v33, v213
	v_lshl_add_u64 v[34:35], s[92:93], 0, v[34:35]
	v_lshl_add_u64 v[34:35], v[34:35], 0, v[178:179]
	v_pk_fma_f32 v[28:29], v[92:93], v[32:33], v[28:29] op_sel_hi:[1,0,1] neg_lo:[1,0,0] neg_hi:[1,0,0]
	v_pk_fma_f32 v[30:31], v[94:95], v[32:33], v[30:31] op_sel_hi:[1,0,1]
	v_pk_fma_f32 v[24:25], v[84:85], v[32:33], v[24:25] op_sel_hi:[1,0,1] neg_lo:[1,0,0] neg_hi:[1,0,0]
	v_pk_fma_f32 v[26:27], v[86:87], v[32:33], v[26:27] op_sel_hi:[1,0,1]
	v_pk_fma_f32 v[30:31], v[32:33], v[30:31], v[90:91] op_sel:[1,0,0]
	v_pk_fma_f32 v[28:29], v[32:33], v[28:29], v[88:89] op_sel:[1,0,0]
	v_pk_fma_f32 v[36:37], v[32:33], v[26:27], v[82:83] op_sel:[1,0,0]
	v_pk_fma_f32 v[26:27], v[32:33], v[24:25], v[80:81] op_sel:[1,0,0]
	v_cvt_pk_f16_f32 v24, v28, v29
	v_cvt_pk_f16_f32 v25, v30, v31
	v_cvt_pk_f16_f32 v26, v26, v27
	v_cvt_pk_f16_f32 v27, v36, v37
	v_pk_fma_f32 v[20:21], v[76:77], v[32:33], v[20:21] op_sel_hi:[1,0,1] neg_lo:[1,0,0] neg_hi:[1,0,0]
	v_pk_fma_f32 v[22:23], v[78:79], v[32:33], v[22:23] op_sel_hi:[1,0,1]
	v_pk_fma_f32 v[16:17], v[68:69], v[32:33], v[16:17] op_sel_hi:[1,0,1] neg_lo:[1,0,0] neg_hi:[1,0,0]
	v_pk_fma_f32 v[18:19], v[70:71], v[32:33], v[18:19] op_sel_hi:[1,0,1]
	global_store_dwordx4 v[34:35], v[24:27], off
	v_pk_fma_f32 v[22:23], v[32:33], v[22:23], v[74:75] op_sel:[1,0,0]
	v_pk_fma_f32 v[20:21], v[32:33], v[20:21], v[72:73] op_sel:[1,0,0]
	v_pk_fma_f32 v[24:25], v[32:33], v[18:19], v[66:67] op_sel:[1,0,0]
	v_pk_fma_f32 v[18:19], v[32:33], v[16:17], v[64:65] op_sel:[1,0,0]
	v_cvt_pk_f16_f32 v16, v20, v21
	v_cvt_pk_f16_f32 v17, v22, v23
	v_cvt_pk_f16_f32 v18, v18, v19
	v_cvt_pk_f16_f32 v19, v24, v25
	global_store_dwordx4 v[34:35], v[16:19], off offset:256
	s_nop 1
	v_add_u32_e32 v16, 0xb0, v176
	v_ashrrev_i32_e32 v17, 31, v16
	v_lshlrev_b64 v[18:19], 12, v[16:17]
	v_lshl_add_u64 v[16:17], v[16:17], 3, s[4:5]
	v_mov_b32_e32 v16, v214
	v_mov_b32_e32 v17, v215
	v_lshl_add_u64 v[18:19], s[92:93], 0, v[18:19]
	v_lshl_add_u64 v[18:19], v[18:19], 0, v[178:179]
	v_pk_fma_f32 v[12:13], v[92:93], v[16:17], v[12:13] op_sel_hi:[1,0,1] neg_lo:[1,0,0] neg_hi:[1,0,0]
	v_pk_fma_f32 v[14:15], v[94:95], v[16:17], v[14:15] op_sel_hi:[1,0,1]
	v_pk_fma_f32 v[8:9], v[84:85], v[16:17], v[8:9] op_sel_hi:[1,0,1] neg_lo:[1,0,0] neg_hi:[1,0,0]
	v_pk_fma_f32 v[10:11], v[86:87], v[16:17], v[10:11] op_sel_hi:[1,0,1]
	v_pk_fma_f32 v[14:15], v[16:17], v[14:15], v[90:91] op_sel:[1,0,0]
	v_pk_fma_f32 v[12:13], v[16:17], v[12:13], v[88:89] op_sel:[1,0,0]
	v_pk_fma_f32 v[20:21], v[16:17], v[10:11], v[82:83] op_sel:[1,0,0]
	v_pk_fma_f32 v[10:11], v[16:17], v[8:9], v[80:81] op_sel:[1,0,0]
	v_cvt_pk_f16_f32 v8, v12, v13
	v_cvt_pk_f16_f32 v9, v14, v15
	v_cvt_pk_f16_f32 v10, v10, v11
	v_cvt_pk_f16_f32 v11, v20, v21
	v_pk_fma_f32 v[4:5], v[76:77], v[16:17], v[4:5] op_sel_hi:[1,0,1] neg_lo:[1,0,0] neg_hi:[1,0,0]
	v_pk_fma_f32 v[6:7], v[78:79], v[16:17], v[6:7] op_sel_hi:[1,0,1]
	v_pk_fma_f32 v[0:1], v[68:69], v[16:17], v[0:1] op_sel_hi:[1,0,1] neg_lo:[1,0,0] neg_hi:[1,0,0]
	v_pk_fma_f32 v[2:3], v[70:71], v[16:17], v[2:3] op_sel_hi:[1,0,1]
	global_store_dwordx4 v[18:19], v[8:11], off
	v_pk_fma_f32 v[6:7], v[16:17], v[6:7], v[74:75] op_sel:[1,0,0]
	v_pk_fma_f32 v[4:5], v[16:17], v[4:5], v[72:73] op_sel:[1,0,0]
	v_pk_fma_f32 v[8:9], v[16:17], v[2:3], v[66:67] op_sel:[1,0,0]
	v_pk_fma_f32 v[2:3], v[16:17], v[0:1], v[64:65] op_sel:[1,0,0]
	v_cvt_pk_f16_f32 v0, v4, v5
	v_cvt_pk_f16_f32 v1, v6, v7
	v_cvt_pk_f16_f32 v2, v2, v3
	v_cvt_pk_f16_f32 v3, v8, v9
	global_store_dwordx4 v[18:19], v[0:3], off offset:256
	s_cbranch_vccnz .LBB0_756
	s_andn2_b64 vcc, exec, s[0:1]
	s_cbranch_vccnz .LBB0_755
	s_barrier
	s_branch .LBB0_755
